# strategy 2 on phase-3a LDS staging loops: gla_pre 4 and lru_pre 9 serialized load-wait-ds_write iterations replaced by all loads issued together + counted waits; rest = v14
# speedup vs baseline: 1.0061x; 1.0061x over previous
; __device__ __forceinline__ void gla_pre(const Params& p, unsigned char* lds) {
;     const int tid = threadIdx.x, lane = tid & 63, w = __builtin_amdgcn_readfirstlane(tid >> 6);
;     float* gu = (float*)(lds + GL_GU); float* gbv = (float*)(lds + GL_GB); f32x2* tab = (f32x2*)(lds + GL_TAB);
;     float* gbuf = (float*)(lds + GL_GBUF); float* tot = (float*)(lds + GL_TOT);
;     bf16_t* qe = (bf16_t*)(lds + GL_QE); bf16_t* ke = (bf16_t*)(lds + GL_KE); bf16_t* att = (bf16_t*)(lds + GL_ATT);
;     const bf16_t* P = (const bf16_t*)(p.ws + WS_P);
;     bf16_t* GQ = (bf16_t*)(p.ws + WS_GQ); bf16_t* GK = (bf16_t*)(p.ws + WS_GK); bf16_t* GA = (bf16_t*)(p.ws + WS_GATT); float* GE = (float*)(p.ws + WS_GBLE);
;     const int i = tid >> 3, dg = tid & 7;
;     const int fr = lane & 15, fq = lane >> 4;
;     __syncthreads();
;     { const f32x2* rt = (const f32x2*)(p.ws + WS_ROPE); for (int e = tid; e < 2048; e += 512) tab[e] = rt[e]; }
;     for (int it = blockIdx.x; it < 32 * 68; it += gridDim.x) {
;         const int chain = it / 68, ci = it % 68; const int dir = chain & 1, h = (chain >> 1) & 3, b = chain >> 3;
.LBB0_283:
	global_load_dwordx2 v[208:209], v[0:1], off
	v_lshl_add_u64 v[0:1], v[0:1], 0, s[2:3]
	global_load_dwordx2 v[210:211], v[0:1], off
	v_lshl_add_u64 v[0:1], v[0:1], 0, s[2:3]
	global_load_dwordx2 v[212:213], v[0:1], off
	v_lshl_add_u64 v[0:1], v[0:1], 0, s[2:3]
	global_load_dwordx2 v[214:215], v[0:1], off
	s_waitcnt vmcnt(3)
	ds_write_b64 v6, v[208:209]
	s_waitcnt vmcnt(2)
	ds_write_b64 v6, v[210:211] offset:4096
	s_waitcnt vmcnt(1)
	ds_write_b64 v6, v[212:213] offset:8192
	s_waitcnt vmcnt(0)
	ds_write_b64 v6, v[214:215] offset:12288
	s_or_b64 exec, exec, s[0:1]
	s_add_u32 s68, s90, 0x10a00000
	s_addc_u32 s69, s91, 0
	s_add_u32 s76, s90, 0xe800000
	s_addc_u32 s77, s91, 0
	s_add_u32 s78, s90, 0x2ac00000
	s_addc_u32 s79, s91, 0
	s_add_u32 s60, s90, 0xc600000
	v_and_b32_e32 v119, 7, v162
	s_addc_u32 s61, s91, 0
	s_add_i32 s1, 0, 0x13400
	v_add_u32_e32 v0, 0, v116
	v_lshlrev_b32_e32 v1, 8, v106
	s_add_u32 s72, s90, 0x2bd00000
	v_sub_u32_e32 v1, v0, v1
	v_lshlrev_b32_e32 v97, 5, v119
	v_lshlrev_b32_e32 v120, 1, v5
	s_addc_u32 s73, s91, 0
	s_movk_i32 s0, 0x7f
	v_lshlrev_b32_e32 v88, 4, v119
	v_mov_b32_e32 v61, 0
	v_add_u32_e32 v113, v1, v97
	s_mov_b32 s43, s1
	v_add3_u32 v114, s1, v120, v97
	v_lshlrev_b32_e32 v90, 7, v106
	v_lshlrev_b32_e32 v98, 3, v119
	v_lshlrev_b32_e32 v1, 6, v106
	s_movk_i32 s1, 0x80
	s_mov_b32 s71, 0
	s_cmpk_gt_i32 s92, 0x87f
	v_and_b32_e32 v59, 0x7f, v162
	v_mov_b32_e32 v89, v61
	v_add_u32_e32 v104, 0, v160
	v_lshlrev_b32_e32 v125, 4, v162
	v_mov_b32_e32 v91, v61
	v_lshlrev_b32_e32 v99, 3, v115
	v_lshl_add_u32 v78, v115, 4, 0
	v_cmp_gt_u32_e64 s[4:5], s1, v162
	v_cmp_lt_u32_e64 s[8:9], s0, v162
	v_readfirstlane_b32 s0, v162
	v_lshlrev_b32_e32 v80, 1, v90
	v_lshlrev_b32_e32 v82, 1, v88
	v_lshlrev_b32_e32 v84, 1, v98
	v_lshlrev_b32_e32 v86, 1, v1
	s_cbranch_scc1 .LBB0_366
	v_add_u32_e32 v1, 0x800, v160
	v_and_b32_e32 v128, 0x1e00, v1
	v_lshlrev_b32_e32 v1, 2, v88
	v_mov_b32_e32 v81, v61
	v_add_u32_e32 v131, v0, v1
	v_and_b32_e32 v0, 16, v125
	s_movk_i32 s2, 0x17f
	v_add_u32_e32 v5, 0x1800, v160
	v_mov_b32_e32 v83, v61
	v_add_u32_e32 v130, 0, v1
	v_lshl_add_u32 v132, v0, 3, 0
	v_cmp_lt_u32_e64 s[16:17], s2, v162
	v_lshl_add_u64 v[0:1], s[76:77], 0, v[80:81]
	v_mov_b32_e32 v87, v61
	s_lshr_b32 s2, s0, 7
	s_lshr_b32 s0, s0, 5
	v_readlane_b32 s1, v241, 0
	v_and_b32_e32 v129, 0x3e00, v5
	v_and_b32_e32 v5, 2, v162
	v_lshl_add_u64 v[64:65], v[0:1], 0, v[82:83]
	v_lshl_add_u64 v[0:1], s[78:79], 0, v[86:87]
	v_mov_b32_e32 v85, v61
	s_and_b32 s0, s0, 2
	s_lshl_b32 s3, s2, 4
	v_lshl_add_u64 v[8:9], s[60:61], 0, v[80:81]
	s_movk_i32 s1, 0xff
	v_lshl_add_u64 v[66:67], v[0:1], 0, v[84:85]
	v_cmp_eq_u32_e32 vcc, 0, v5
	v_or_b32_e32 v1, s3, v110
	v_or_b32_e32 v5, s3, v108
	s_movk_i32 s3, 0x110
	v_lshl_or_b32 v7, s0, 4, v108
	v_cmp_lt_u32_e64 s[12:13], s1, v162
	v_lshl_add_u64 v[62:63], v[8:9], 0, v[82:83]
	s_add_i32 s1, 0, 0x19c00
	v_mul_lo_u32 v5, v5, s3
	v_or_b32_e32 v8, 16, v7
	s_movk_i32 s3, 0x90
	s_cmp_le_u32 s0, s2
	v_mul_lo_u32 v10, v1, s3
	v_or_b32_e32 v11, 1, v1
	v_or_b32_e32 v12, 2, v1
	v_or_b32_e32 v13, 3, v1
	v_lshlrev_b32_e32 v14, 1, v8
	s_mov_b64 s[52:53], s[74:75]
	v_add3_u32 v126, s1, v4, v84
	v_cmp_gt_u32_e64 s[18:19], v8, v1
	s_cselect_b64 s[74:75], -1, 0
	s_cmp_lt_u32 s0, s2
	v_add3_u32 v81, s1, v10, v14
	v_cmp_gt_u32_e64 s[20:21], v8, v11
	v_cmp_gt_u32_e64 s[22:23], v8, v12
	v_cmp_gt_u32_e64 s[24:25], v8, v13
	v_lshl_add_u32 v8, v7, 1, s1
	v_readlane_b32 s0, v241, 33
	v_xor_b32_e32 v6, 32, v88
	v_lshl_add_u32 v4, v59, 2, 0
	v_cndmask_b32_e64 v68, 1.0, -1.0, vcc
	v_lshl_add_u32 v0, v99, 1, s43
	v_mul_u32_u24_e32 v9, 0x110, v7
	v_readlane_b32 s1, v241, 34
	v_readlane_b32 s2, v241, 35
	s_mov_b32 s0, s92
	s_mov_b32 s67, s34
	s_mov_b32 s66, s33
	s_mov_b32 s63, s15
	s_mov_b64 s[64:65], s[94:95]
	s_mov_b32 s62, s93
	s_mov_b64 s[56:57], s[96:97]
	v_cmp_gt_u32_e64 s[10:11], 4, v119
	v_cmp_eq_u32_e64 s[14:15], 63, v106
	v_and_b32_e32 v127, 0xe00, v160
	s_mov_b64 s[54:55], s[76:77]
	s_mov_b64 s[58:59], s[78:79]
	s_cselect_b64 s[76:77], -1, 0
	v_add_u32_e32 v85, 0x90, v81
	v_add_u32_e32 v87, 0x120, v81
	v_add_u32_e32 v133, 0x1b0, v81
	v_cmp_gt_u32_e64 s[26:27], v7, v1
	v_cmp_gt_u32_e64 s[28:29], v7, v11
	v_cmp_gt_u32_e64 s[30:31], v7, v12
	v_cmp_gt_u32_e64 s[34:35], v7, v13
	v_mov_b32_e32 v69, v68
	s_lshl_b32 s97, s92, 6
	v_readlane_b32 s3, v241, 36
	s_lshl_b32 s79, s2, 6
	s_movk_i32 s83, 0x2200
	v_lshlrev_b32_e32 v70, 1, v6
	s_mov_b32 s40, 0xbfb8aa3b
	s_mov_b32 s41, 0x800000
	s_mov_b32 s82, 0x3f317217
	s_mov_b32 s96, 0x7f800000
	s_mov_b32 s78, 0x3d800000
	v_add_u32_e32 v134, v4, v2
	v_add_u32_e32 v135, v4, v3
	s_mov_b32 s80, 0x3db504f3
	v_add_u32_e32 v136, v8, v10
	v_mov_b32_e32 v137, 0x41b17218
	v_add_u32_e32 v138, v78, v5
	v_add_u32_e32 v139, v0, v9
	v_writelane_b32 v241, s0, 37
	s_nop 1
	v_writelane_b32 v241, s1, 38
	s_branch .LBB0_287

; __device__ __forceinline__ void lru_pre(const Params& p, unsigned char* lds) {
;     ...
;     { const u32x4* img = (const u32x4*)(p.ws + WS_LRUW + (size_t)(dir * 8 + g) * 2 * (128 * 136 * 2)); u32x4* dst = (u32x4*)Ba;
;       for (int e = tid; e < 2 * 34816 / 16; e += 512) dst[e] = img[e]; }
;     for (int e = tid; e < 640; e += 512) { const int j = e >> 7, c = e & 127; cw[e] = j < 4 ? p.conv_w[j * 1024 + c0 + c] : p.conv_b[c0 + c]; }
.LBB0_367:
	global_load_dwordx4 v[208:211], v[0:1], off
	v_lshl_add_u64 v[0:1], v[0:1], 0, s[2:3]
	global_load_dwordx4 v[212:215], v[0:1], off
	v_lshl_add_u64 v[0:1], v[0:1], 0, s[2:3]
	global_load_dwordx4 v[216:219], v[0:1], off
	v_lshl_add_u64 v[0:1], v[0:1], 0, s[2:3]
	global_load_dwordx4 v[220:223], v[0:1], off
	v_lshl_add_u64 v[0:1], v[0:1], 0, s[2:3]
	global_load_dwordx4 v[224:227], v[0:1], off
	v_lshl_add_u64 v[0:1], v[0:1], 0, s[2:3]
	global_load_dwordx4 v[228:231], v[0:1], off
	v_lshl_add_u64 v[0:1], v[0:1], 0, s[2:3]
	global_load_dwordx4 v[232:235], v[0:1], off
	v_lshl_add_u64 v[0:1], v[0:1], 0, s[2:3]
	global_load_dwordx4 v[236:239], v[0:1], off
	v_lshl_add_u64 v[0:1], v[0:1], 0, s[2:3]
	v_cmp_gt_u32_e32 vcc, 0x100, v162
	s_and_saveexec_b64 s[2:3], vcc
	global_load_dwordx4 v[4:7], v[0:1], off
	s_mov_b64 exec, s[2:3]
	s_waitcnt vmcnt(7)
	ds_write_b128 v2, v[208:211]
	s_waitcnt vmcnt(6)
	ds_write_b128 v2, v[212:215] offset:8192
	s_waitcnt vmcnt(5)
	ds_write_b128 v2, v[216:219] offset:16384
	s_waitcnt vmcnt(4)
	ds_write_b128 v2, v[220:223] offset:24576
	s_waitcnt vmcnt(3)
	ds_write_b128 v2, v[224:227] offset:32768
	s_waitcnt vmcnt(2)
	ds_write_b128 v2, v[228:231] offset:40960
	s_waitcnt vmcnt(1)
	ds_write_b128 v2, v[232:235] offset:49152
	s_waitcnt vmcnt(0)
	ds_write_b128 v2, v[236:239] offset:57344
	v_add_u32_e32 v2, 0x10000, v2
	s_and_saveexec_b64 s[2:3], vcc
	ds_write_b128 v2, v[4:7]
	s_mov_b64 exec, s[2:3]
	s_or_b64 exec, exec, s[0:1]
	s_lshl_b32 s0, s92, 7
	s_and_b32 s14, s0, 0x380
	s_movk_i32 s0, 0x280
	v_cmp_gt_u32_e32 vcc, s0, v162
	v_readfirstlane_b32 s8, v162
	s_and_saveexec_b64 s[0:1], vcc
	s_cbranch_execz .LBB0_371
	v_or_b32_e32 v0, s14, v59
	v_readlane_b32 s16, v241, 17
	v_mov_b32_e32 v3, 0
	v_lshlrev_b32_e32 v2, 2, v0
	v_readlane_b32 s17, v241, 18
	v_add_u32_e32 v1, 0, v160
	v_add_u32_e32 v1, 0x1d800, v1
	v_lshl_add_u64 v[4:5], s[16:17], 0, v[2:3]
	s_mov_b64 s[2:3], 0
	s_movk_i32 s9, 0x200
	s_movk_i32 s10, 0xc00
	s_movk_i32 s11, 0x7f
	v_mov_b32_e32 v6, v162
	v_readlane_b32 s18, v241, 19
	v_readlane_b32 s19, v241, 20
	v_readlane_b32 s20, v241, 21
	v_readlane_b32 s21, v241, 22
	v_readlane_b32 s22, v241, 23
	v_readlane_b32 s23, v241, 24
	v_readlane_b32 s24, v241, 25
	v_readlane_b32 s25, v241, 26
	v_readlane_b32 s26, v241, 27
	v_readlane_b32 s27, v241, 28
	v_readlane_b32 s28, v241, 29
	v_readlane_b32 s29, v241, 30
	v_readlane_b32 s30, v241, 31
	v_readlane_b32 s31, v241, 32
